# attention tile loop: near-tile bias table reads batched under one wait, max tree as v_max3 without canonicalize, bias-constant read no longer waited separately
# speedup vs baseline: 1.0218x; 1.0052x over previous
.LBB0_514:
	s_cmp_gt_i32 s23, s86
	s_cbranch_scc1 .LBB0_510
	v_mov_b32_e32 v233, s18
	ds_read_b32 v233, v233
	s_mul_i32 s13, s27, 0x6000
	s_add_i32 s13, s13, 0
	s_cmpk_gt_i32 s25, 0x70
	s_cselect_b64 vcc, -1, 0
	s_add_i32 s28, s13, 0x2000
	v_add_u32_e32 v156, s28, v205
	v_add_u32_e32 v0, s13, v205
	v_add_u32_e32 v82, s13, v206
	v_add_u32_e32 v83, s13, v207
	v_add_u32_e32 v84, s13, v208
	ds_read_b128 v[158:161], v209
	ds_read_b128 v[162:165], v209 offset:32
	ds_read_b128 v[166:169], v209 offset:64
	ds_read_b128 v[170:173], v209 offset:96
	ds_read_b128 v[174:177], v0
	ds_read_b128 v[178:181], v82
	ds_read_b128 v[182:185], v83
	ds_read_b128 v[186:189], v84
	ds_read_b128 v[190:193], v0 offset:4096
	ds_read_b128 v[194:197], v82 offset:4096
	ds_read_b128 v[198:201], v83 offset:4096
	ds_read_b128 v[220:223], v84 offset:4096
	s_waitcnt lgkmcnt(0)
	v_cndmask_b32_e32 v233, 0, v233, vcc
	v_xor_b32_e32 v0, 32, v156
	v_sub_f32_e32 v66, v233, v154
	ds_read_b128 v[126:129], v156
	ds_read_b128 v[122:125], v156 offset:4096
	ds_read_b128 v[118:121], v156 offset:8192
	ds_read_b128 v[114:117], v156 offset:12288
	ds_read_b128 v[110:113], v0
	ds_read_b128 v[106:109], v0 offset:4096
	ds_read_b128 v[102:105], v0 offset:8192
	ds_read_b128 v[98:101], v0 offset:12288
	v_mov_b32_e32 v67, v66
	v_mov_b32_e32 v68, v66
	v_mov_b32_e32 v69, v66
	v_mov_b32_e32 v70, v66
	v_mov_b32_e32 v71, v66
	v_mov_b32_e32 v72, v66
	v_mov_b32_e32 v73, v66
	v_mov_b32_e32 v74, v66
	v_mov_b32_e32 v75, v66
	v_mov_b32_e32 v76, v66
	v_mov_b32_e32 v77, v66
	v_mov_b32_e32 v78, v66
	v_mov_b32_e32 v79, v66
	v_mov_b32_e32 v80, v66
	v_mov_b32_e32 v81, v66
	s_nop 1
	v_mfma_f32_32x32x16_bf16 v[82:97], v[174:177], v[158:161], v[66:81]
	s_and_b64 vcc, exec, vcc
	v_mfma_f32_32x32x16_bf16 v[66:81], v[190:193], v[158:161], v[66:81]
	v_mfma_f32_32x32x16_bf16 v[82:97], v[178:181], v[162:165], v[82:97]
	v_mfma_f32_32x32x16_bf16 v[66:81], v[194:197], v[162:165], v[66:81]
	v_mfma_f32_32x32x16_bf16 v[82:97], v[182:185], v[166:169], v[82:97]
	v_mfma_f32_32x32x16_bf16 v[66:81], v[198:201], v[166:169], v[66:81]
	v_mfma_f32_32x32x16_bf16 v[82:97], v[186:189], v[170:173], v[82:97]
	v_mfma_f32_32x32x16_bf16 v[66:81], v[220:223], v[170:173], v[66:81]
	s_cbranch_vccnz .LBB0_517
	v_add_u32_e32 v0, s26, v214
	v_add_u32_e32 v157, 0x18094, v0
	ds_read2_b32 v[158:159], v157 offset0:58 offset1:59
	ds_read2_b32 v[160:161], v157 offset0:26 offset1:27
	ds_read2_b32 v[162:163], v157 offset0:56 offset1:57
	ds_read2_b32 v[164:165], v157 offset0:24 offset1:25
	ds_read2_b32 v[166:167], v157 offset0:50 offset1:51
	ds_read2_b32 v[168:169], v157 offset0:18 offset1:19
	ds_read2_b32 v[174:175], v157 offset0:48 offset1:49
	ds_read2_b32 v[176:177], v157 offset0:16 offset1:17
	ds_read2_b32 v[178:179], v157 offset0:42 offset1:43
	ds_read2_b32 v[180:181], v157 offset0:10 offset1:11
	ds_read2_b32 v[182:183], v157 offset0:40 offset1:41
	ds_read2_b32 v[184:185], v157 offset0:8 offset1:9
	ds_read2_b32 v[190:191], v157 offset0:34 offset1:35
	ds_read2_b32 v[192:193], v157 offset0:2 offset1:3
	ds_read2_b32 v[194:195], v157 offset0:32 offset1:33
	ds_read2_b32 v[196:197], v157 offset0:0 offset1:1
	s_waitcnt lgkmcnt(0)
	v_pk_add_f32 v[82:83], v[82:83], v[158:159] op_sel:[0,1] op_sel_hi:[1,0]
	v_pk_add_f32 v[66:67], v[66:67], v[160:161] op_sel:[0,1] op_sel_hi:[1,0]
	v_pk_add_f32 v[84:85], v[84:85], v[162:163] op_sel:[0,1] op_sel_hi:[1,0]
	v_pk_add_f32 v[68:69], v[68:69], v[164:165] op_sel:[0,1] op_sel_hi:[1,0]
	v_pk_add_f32 v[86:87], v[86:87], v[166:167] op_sel:[0,1] op_sel_hi:[1,0]
	v_pk_add_f32 v[70:71], v[70:71], v[168:169] op_sel:[0,1] op_sel_hi:[1,0]
	v_pk_add_f32 v[88:89], v[88:89], v[174:175] op_sel:[0,1] op_sel_hi:[1,0]
	v_pk_add_f32 v[72:73], v[72:73], v[176:177] op_sel:[0,1] op_sel_hi:[1,0]
	v_pk_add_f32 v[90:91], v[90:91], v[178:179] op_sel:[0,1] op_sel_hi:[1,0]
	v_pk_add_f32 v[74:75], v[74:75], v[180:181] op_sel:[0,1] op_sel_hi:[1,0]
	v_pk_add_f32 v[92:93], v[92:93], v[182:183] op_sel:[0,1] op_sel_hi:[1,0]
	v_pk_add_f32 v[76:77], v[76:77], v[184:185] op_sel:[0,1] op_sel_hi:[1,0]
	v_pk_add_f32 v[94:95], v[94:95], v[190:191] op_sel:[0,1] op_sel_hi:[1,0]
	v_pk_add_f32 v[78:79], v[78:79], v[192:193] op_sel:[0,1] op_sel_hi:[1,0]
	v_pk_add_f32 v[96:97], v[96:97], v[194:195] op_sel:[0,1] op_sel_hi:[1,0]
	v_pk_add_f32 v[80:81], v[80:81], v[196:197] op_sel:[0,1] op_sel_hi:[1,0]
.LBB0_517:
	s_nop 10
	v_max3_f32 v0, v82, v66, v83
	v_max3_f32 v157, v67, v84, v68
	v_max3_f32 v0, v0, v85, v69
	v_max3_f32 v157, v157, v86, v70
	v_max3_f32 v0, v0, v87, v71
	v_max3_f32 v157, v157, v88, v72
	v_max3_f32 v0, v0, v89, v73
	v_max3_f32 v157, v157, v90, v74
	v_max3_f32 v0, v0, v91, v75
	v_max3_f32 v157, v157, v92, v76
	v_max3_f32 v0, v0, v93, v77
	v_max3_f32 v157, v157, v94, v78
	v_max3_f32 v0, v0, v95, v79
	v_max3_f32 v157, v157, v96, v80
	v_max3_f32 v0, v0, v97, v81
	v_max_f32_e32 v0, v0, v157
	v_mov_b32_e32 v157, v0
	s_nop 1
	v_permlane32_swap_b32_e32 v0, v157
	s_cmp_eq_u32 s26, 0
	s_cselect_b64 s[44:45], -1, 0
	s_cmp_lg_u32 s26, 0
	v_max_f32_e32 v157, v0, v157
	s_cbranch_scc0 .LBB0_524
	s_mov_b32 s13, 0x41000000
	v_cmp_lt_f32_e32 vcc, s13, v157
	s_mov_b64 s[50:51], 0
	s_mov_b64 s[48:49], 0
	s_cbranch_vccz .LBB0_520
	v_max_f32_e32 v0, v157, v157
	v_max_f32_e32 v0, 0, v0
	s_mov_b64 s[48:49], -1
